# scan rank-2 state update as two K=1 outer products on v_mfma_f32_4x4x1_16b_f32 (exact f32, half the matrix-pipe time of the 16x16x4 K-padded form)
# speedup vs baseline: 1.0178x; 1.0086x over previous
; DI void scan_item(const Params& p, char* smem, int b, int h, bool prompt, const int g_wave) {
;     ...
;     const int li = lane & 15, g = lane >> 4, irow = wid * 16 + li;
;     f32x2 S0[4], S1[4];
;     if (prompt) { for (int e = 0; e < 4; ++e) { S0[e] = (f32x2){0.f, 0.f}; S1[e] = (f32x2){0.f, 0.f}; } }
;     else {
;       const float* s0 = p.state_wkv + ((size_t)(b * 16 + h) * 64 + irow) * 64 + 8 * g;
;       for (int e = 0; e < 4; ++e) { S0[e] = (f32x2){s0[2 * e], s0[2 * e + 1]}; S1[e] = (f32x2){s0[32 + 2 * e], s0[32 + 2 * e + 1]}; }
;     }
;     const int abf_off = ((lane & 3) == 1 ? 12288 : 8192) + 16 * g;
;     __syncthreads();
; #pragma unroll 1
;     for (int k = 0; k < nch; ++k) {
;       const char* set = smem + (k & 1) * SETB;
;       const float* bW = (const float*)set + 8 * g;
;       const char* bA = set + abf_off;
;       const float* bV = (const float*)(set + 40960) + irow;
;       float* Yp = (float*)(set + 49152) + irow;
;       const float2* BK = (const float2*)(set + 57472);
;     ...
;       f32x4v Pw0, Pw1, Pw2, Pw3, Pb0, Pb1, Pb2, Pb3, Pk0, Pk1, Pk2, Pk3; bf16x8 Pa0, Pa1; float Pv; float2 Ps;
;       f32x4v Qw0, Qw1, Qw2, Qw3, Qb0, Qb1, Qb2, Qb3, Qk0, Qk1, Qk2, Qk3; bf16x8 Qa0, Qa1; float Qv; float2 Qs;
;       LOADV(P, 0);
; #pragma unroll 1
;       for (int t = 0; t < 32; t += 2) {
;         LOADV(Q, t + 1);
;         STEP(P, t);
;         LOADV(P, t + 2);
;         STEP(Q, t + 1);
;       }
;     ...
;       asm volatile("s_waitcnt lgkmcnt(0)" ::: "memory");
;       __builtin_amdgcn_s_barrier();
;       asm volatile("" ::: "memory");
;     }
;     float* so = p.out + (prompt ? O_WKVP : O_WKVS) + ((size_t)(b * 16 + h) * 64 + irow) * 64 + 8 * g;
;     *(float4*)so = make_float4(S0[0].x, S0[0].y, S0[1].x, S0[1].y); *(float4*)(so + 4) = make_float4(S0[2].x, S0[2].y, S0[3].x, S0[3].y);
;     *(float4*)(so + 32) = make_float4(S1[0].x, S1[0].y, S1[1].x, S1[1].y); *(float4*)(so + 36) = make_float4(S1[2].x, S1[2].y, S1[3].x, S1[3].y);
.LBB0_794:
	v_and_b32_e32 v21, 3, v119
	v_mov_b32_e32 v22, 0x2000
	v_mov_b32_e32 v23, 0x3000
	v_cmp_eq_u32_e32 vcc, 1, v21
	v_lshlrev_b32_e32 v83, 2, v21
	v_lshrrev_b32_e32 v21, 1, v82
	v_cndmask_b32_e32 v77, v22, v23, vcc
	v_add_u32_e32 v77, v77, v21
	v_mov_b32_e32 v22, 0x4000
	v_add3_u32 v83, v83, v82, v22
	v_add_u32_e32 v27, 0x2000, v83
	v_lshlrev_b32_e32 v84, 2, v79
	v_add_u32_e32 v84, 0xa000, v84
	v_mov_b32_e32 v85, v82
	s_mov_b32 s0, 0
	s_waitcnt vmcnt(0)
	s_barrier
.LBB0_795:
	s_bitcmp1_b32 s0, 0
	s_cselect_b32 s4, 0xe180, 0
	s_add_i32 s1, s4, 16
	v_add_u32_e32 v88, s1, v85
	v_add_u32_e32 v86, s1, v83
	v_add_u32_e32 v26, s1, v27
	v_add_u32_e32 v89, s1, v77
	v_add_u32_e32 v87, s1, v84
	s_add_i32 s1, s1, 0xe080
	v_mov_b32_e32 v111, s1
	ds_read_b128 v[52:55], v88
	ds_read_b128 v[40:43], v88 offset:64
	ds_read_b128 v[28:31], v88 offset:128
	ds_read_b128 v[20:23], v88 offset:192
	ds_read2_b32 v[60:61], v86 offset0:0 offset1:16
	ds_read2_b32 v[62:63], v86 offset0:32 offset1:48
	ds_read2_b32 v[32:33], v26 offset0:0 offset1:16
	ds_read2_b32 v[34:35], v26 offset0:32 offset1:48
	ds_read_b64 v[72:73], v89
	ds_read_b64 v[74:75], v89 offset:32
	ds_read_b64 v[68:69], v89 offset:64
	ds_read_b64 v[70:71], v89 offset:96
	ds_read_b32 v78, v87
	ds_read_b64 v[80:81], v111
	s_mov_b32 s4, -2
.LBB0_796:
	ds_read_b128 v[90:93], v88 offset:256
	ds_read_b128 v[94:97], v88 offset:320
	ds_read_b128 v[98:101], v88 offset:384
	ds_read_b128 v[102:105], v88 offset:448
	ds_read2_b32 v[106:107], v86 offset0:64 offset1:80
	ds_read2_b32 v[108:109], v86 offset0:96 offset1:112
	ds_read2_b32 v[36:37], v26 offset0:64 offset1:80
	ds_read2_b32 v[38:39], v26 offset0:96 offset1:112
	ds_read_b64 v[138:139], v89 offset:128
	ds_read_b64 v[140:141], v89 offset:160
	ds_read_b64 v[142:143], v89 offset:192
	ds_read_b64 v[144:145], v89 offset:224
	ds_read_b32 v154, v87 offset:256
	ds_read_b64 v[156:157], v111 offset:8
	v_cvt_pk_bf16_f32 v146, v16, v17
	v_cvt_pk_bf16_f32 v147, v18, v19
	v_cvt_pk_bf16_f32 v148, v12, v13
	v_cvt_pk_bf16_f32 v149, v14, v15
	v_cvt_pk_bf16_f32 v150, v4, v5
	v_cvt_pk_bf16_f32 v151, v6, v7
	v_cvt_pk_bf16_f32 v152, v8, v9
	v_cvt_pk_bf16_f32 v153, v10, v11
	s_waitcnt lgkmcnt(14)
	v_mfma_f32_16x16x32_bf16 v[72:75], v[72:75], v[146:149], 0
	v_mfma_f32_16x16x32_bf16 v[68:71], v[68:71], v[150:153], v[72:75]
	v_pk_mul_f32 v[16:17], v[16:17], v[52:53]
	v_pk_mul_f32 v[18:19], v[18:19], v[54:55]
	v_pk_mul_f32 v[12:13], v[12:13], v[40:41]
	v_pk_mul_f32 v[14:15], v[14:15], v[42:43]
	v_pk_mul_f32 v[4:5], v[4:5], v[28:29]
	v_pk_mul_f32 v[6:7], v[6:7], v[30:31]
	v_pk_mul_f32 v[8:9], v[8:9], v[20:21]
	v_pk_mul_f32 v[10:11], v[10:11], v[22:23]
	v_mfma_f32_4x4x1_16b_f32 v[16:19], v32, v78, v[16:19]
	v_mfma_f32_4x4x1_16b_f32 v[12:15], v33, v78, v[12:15]
	v_mfma_f32_4x4x1_16b_f32 v[4:7], v34, v78, v[4:7]
	v_mfma_f32_4x4x1_16b_f32 v[8:11], v35, v78, v[8:11]
	v_fma_f32 v146, v78, v81, v69
	v_fmac_f32_e32 v146, v68, v80
	v_mfma_f32_4x4x1_16b_f32 v[16:19], v60, v68, v[16:19]
	v_mfma_f32_4x4x1_16b_f32 v[12:15], v61, v68, v[12:15]
	v_mfma_f32_4x4x1_16b_f32 v[4:7], v62, v68, v[4:7]
	v_mfma_f32_4x4x1_16b_f32 v[8:11], v63, v68, v[8:11]
	ds_write_b32 v87, v146 offset:8192
	ds_read_b128 v[52:55], v88 offset:512
	ds_read_b128 v[40:43], v88 offset:576
	ds_read_b128 v[28:31], v88 offset:640
	ds_read_b128 v[20:23], v88 offset:704
	ds_read2_b32 v[60:61], v86 offset0:128 offset1:144
	ds_read2_b32 v[62:63], v86 offset0:160 offset1:176
	ds_read2_b32 v[32:33], v26 offset0:128 offset1:144
	ds_read2_b32 v[34:35], v26 offset0:160 offset1:176
	ds_read_b64 v[72:73], v89 offset:256
	ds_read_b64 v[74:75], v89 offset:288
	ds_read_b64 v[68:69], v89 offset:320
	ds_read_b64 v[70:71], v89 offset:352
	ds_read_b32 v78, v87 offset:512
	ds_read_b64 v[80:81], v111 offset:16
	v_cvt_pk_bf16_f32 v146, v16, v17
	v_cvt_pk_bf16_f32 v147, v18, v19
	v_cvt_pk_bf16_f32 v148, v12, v13
	v_cvt_pk_bf16_f32 v149, v14, v15
	v_cvt_pk_bf16_f32 v150, v4, v5
	v_cvt_pk_bf16_f32 v151, v6, v7
	v_cvt_pk_bf16_f32 v152, v8, v9
	v_cvt_pk_bf16_f32 v153, v10, v11
	s_waitcnt lgkmcnt(14)
	v_mfma_f32_16x16x32_bf16 v[138:141], v[138:141], v[146:149], 0
	v_mfma_f32_16x16x32_bf16 v[142:145], v[142:145], v[150:153], v[138:141]
	v_pk_mul_f32 v[16:17], v[16:17], v[90:91]
	v_pk_mul_f32 v[18:19], v[18:19], v[92:93]
	v_pk_mul_f32 v[12:13], v[12:13], v[94:95]
	v_pk_mul_f32 v[14:15], v[14:15], v[96:97]
	v_pk_mul_f32 v[4:5], v[4:5], v[98:99]
	v_pk_mul_f32 v[6:7], v[6:7], v[100:101]
	v_pk_mul_f32 v[8:9], v[8:9], v[102:103]
	v_pk_mul_f32 v[10:11], v[10:11], v[104:105]
	v_mfma_f32_4x4x1_16b_f32 v[16:19], v36, v154, v[16:19]
	v_mfma_f32_4x4x1_16b_f32 v[12:15], v37, v154, v[12:15]
	v_mfma_f32_4x4x1_16b_f32 v[4:7], v38, v154, v[4:7]
	v_mfma_f32_4x4x1_16b_f32 v[8:11], v39, v154, v[8:11]
	v_fma_f32 v146, v154, v157, v143
	v_fmac_f32_e32 v146, v142, v156
	v_mfma_f32_4x4x1_16b_f32 v[16:19], v106, v142, v[16:19]
	v_mfma_f32_4x4x1_16b_f32 v[12:15], v107, v142, v[12:15]
	v_mfma_f32_4x4x1_16b_f32 v[4:7], v108, v142, v[4:7]
	v_mfma_f32_4x4x1_16b_f32 v[8:11], v109, v142, v[8:11]
	ds_write_b32 v87, v146 offset:8448
	s_add_i32 s4, s4, 2
	v_add_u32_e32 v88, 0x200, v88
	v_add_u32_e32 v86, 0x200, v86
	v_add_u32_e32 v26, 0x200, v26
	v_add_u32_e32 v89, 0x100, v89
	v_add_u32_e32 v87, 0x200, v87
	v_add_u32_e32 v111, 16, v111
	s_cmp_gt_u32 s4, 29
	s_cbranch_scc0 .LBB0_796
	s_waitcnt lgkmcnt(0)
	s_barrier
	s_add_i32 s0, s0, 1
	s_cmp_eq_u32 s0, s43
	s_cbranch_scc0 .LBB0_795
	s_and_b64 s[0:1], s[38:39], exec
	s_mov_b32 s0, 0x30200000
	s_cselect_b32 s0, s0, 0x30819000
	s_add_u32 s4, s70, s0
	s_addc_u32 s5, s71, 0
	s_ashr_i32 s43, s42, 31
	s_lshl_b64 s[0:1], s[42:43], 14
	s_add_u32 s0, s4, s0
	s_addc_u32 s1, s5, s1
	s_nop 7
	s_nop 3
	v_lshl_add_u64 v[20:21], s[0:1], 0, v[2:3]
	v_mov_b32_e32 v77, v3
	v_lshl_add_u64 v[20:21], v[20:21], 0, v[76:77]
	global_store_dwordx4 v[20:21], v[16:19], off
	global_store_dwordx4 v[20:21], v[12:15], off offset:64
	global_store_dwordx4 v[20:21], v[4:7], off offset:128
	global_store_dwordx4 v[20:21], v[8:11], off offset:192
	s_branch .LBB0_680
